# adds: gain-vector loads of the leftover-row norm phases hoisted (no per-chunk vmcnt(0) store drains)
# baseline (speedup 1.0000x reference)
;   __device__ __forceinline__ bf16* h() const { unsigned o_ = (unsigned)(OFF_h); asm volatile("" : "+s"(o_)); return (bf16*)(ws + o_); }
;   __device__ __forceinline__ bf16* y() const { unsigned o_ = (unsigned)(OFF_y); asm volatile("" : "+s"(o_)); return (bf16*)(ws + o_); }
;   __device__ __forceinline__ float* tmp() const { unsigned o_ = (unsigned)(OFF_U + (size_t)100663296); asm volatile("" : "+s"(o_)); return (float*)(ws + o_); }
; __device__ __forceinline__ float lo16(unsigned v) { return __uint_as_float(v << 16); }
; __device__ __forceinline__ float hi16(unsigned v) { return __uint_as_float(v & 0xffff0000u); }
; __device__ void phase_norm(const P& p, const float* gpost, const float* gnext, bool last, int rowbeg, int rowend) {
;     ...
;   for (int row = rowbeg + gw; row < rowend; row += nw) {
;     const int b = row / RB, t = row % RB + PADB;
;     float4 m[4], hv[4];
;     float ss = 0.f;
; #pragma unroll
;     for (int i = 0; i < 4; ++i) {
;       m[i] = *(const float4*)(p.tmp() + (size_t)row * D + i * 256 + lane * 4);
;       { const uint2 hb_ = *(const uint2*)(p.h() + (size_t)row * D + i * 256 + lane * 4); hv[i] = make_float4(lo16(hb_.x), hi16(hb_.x), lo16(hb_.y), hi16(hb_.y)); }
;       ss += m[i].x * m[i].x + m[i].y * m[i].y + m[i].z * m[i].z + m[i].w * m[i].w;
;     }
;     ss = wave_sum(ss);
;     const float rs = rsqrtf(ss * (1.f / D) + EPS);
;     float ss2 = 0.f;
; #pragma unroll
;     for (int i = 0; i < 4; ++i) {
;       float4 gg = *(const float4*)(gpost + i * 256 + lane * 4);
;       hv[i].x += m[i].x * rs * gg.x; hv[i].y += m[i].y * rs * gg.y; hv[i].z += m[i].z * rs * gg.z; hv[i].w += m[i].w * rs * gg.w;
;       ss2 += hv[i].x * hv[i].x + hv[i].y * hv[i].y + hv[i].z * hv[i].z + hv[i].w * hv[i].w;
.LBB0_929:
	s_mov_b32 s4, 0xc180000
	s_add_u32 s4, s76, s4
	s_addc_u32 s5, s77, 0
	v_lshl_add_u64 v[0:1], s[4:5], 0, v[16:17]
	s_mov_b32 s4, s97
	global_load_dwordx4 v[4:7], v[0:1], off
	s_add_u32 s4, s76, s4
	s_addc_u32 s5, s77, 0
	v_lshl_add_u64 v[0:1], s[4:5], 0, v[14:15]
	s_mov_b32 s4, 0xc180000
	global_load_dwordx2 v[26:27], v[0:1], off
	s_add_u32 s4, s76, s4
	s_addc_u32 s5, s77, 0
	v_lshl_add_u64 v[0:1], s[4:5], 0, v[16:17]
	s_mov_b32 s4, s97
	global_load_dwordx4 v[0:3], v[0:1], off offset:1024
	s_add_u32 s4, s76, s4
	s_addc_u32 s5, s77, 0
	v_lshl_add_u64 v[18:19], s[4:5], 0, v[14:15]
	global_load_dwordx2 v[18:19], v[18:19], off offset:512
	global_load_dwordx4 v[60:63], v[10:11], off
	global_load_dwordx4 v[64:67], v[10:11], off offset:1024
	global_load_dwordx4 v[68:71], v[10:11], off offset:2048
	global_load_dwordx4 v[72:75], v[10:11], off offset:3072
	global_load_dwordx4 v[76:79], v[12:13], off
	global_load_dwordx4 v[80:83], v[12:13], off offset:1024
	global_load_dwordx4 v[84:87], v[12:13], off offset:2048
	global_load_dwordx4 v[88:91], v[12:13], off offset:3072
	s_mov_b32 s4, 0xc180000
	s_add_u32 s4, s76, s4
	s_addc_u32 s5, s77, 0
	v_add_u32_e32 v8, s90, v8
	s_waitcnt vmcnt(11)
	v_mov_b32_e32 v28, v4
	s_waitcnt vmcnt(10)
	v_lshlrev_b32_e32 v24, 16, v26
	v_and_b32_e32 v22, 0xffff0000, v26
	v_lshlrev_b32_e32 v20, 16, v27
	v_mov_b32_e32 v26, v6
	s_waitcnt vmcnt(9)
	v_mov_b32_e32 v29, v0
	v_mov_b32_e32 v0, v5
	v_pk_mul_f32 v[4:5], v[0:1], v[0:1]
	s_waitcnt vmcnt(8)
	v_lshlrev_b32_e32 v25, 16, v18
	v_and_b32_e32 v23, 0xffff0000, v18
	v_and_b32_e32 v18, 0xffff0000, v27
	v_pk_fma_f32 v[4:5], v[28:29], v[28:29], v[4:5]
	v_mov_b32_e32 v27, v2
	v_pk_fma_f32 v[4:5], v[26:27], v[26:27], v[4:5]
	v_mov_b32_e32 v2, v7
	v_pk_fma_f32 v[46:47], v[2:3], v[2:3], v[4:5]
	v_lshl_add_u64 v[4:5], s[4:5], 0, v[16:17]
	s_mov_b32 s4, s97
	global_load_dwordx4 v[42:45], v[4:5], off offset:2048
	s_add_u32 s4, s76, s4
	s_addc_u32 s5, s77, 0
	v_lshl_add_u64 v[4:5], s[4:5], 0, v[14:15]
	s_mov_b32 s4, 0xc180000
	global_load_dwordx2 v[38:39], v[4:5], off offset:1024
	s_add_u32 s4, s76, s4
	s_addc_u32 s5, s77, 0
	v_lshl_add_u64 v[4:5], s[4:5], 0, v[16:17]
	s_mov_b32 s4, s97
	global_load_dwordx4 v[4:7], v[4:5], off offset:3072
	s_add_u32 s4, s76, s4
	s_addc_u32 s5, s77, 0
	v_lshl_add_u64 v[30:31], s[4:5], 0, v[14:15]
	global_load_dwordx2 v[30:31], v[30:31], off offset:1536
	v_add_f32_e32 v9, v46, v47
	v_lshlrev_b32_e32 v21, 16, v19
	v_and_b32_e32 v19, 0xffff0000, v19
	s_mov_b32 s4, s97
	v_lshl_add_u64 v[16:17], v[16:17], 0, s[16:17]
	s_waitcnt vmcnt(3)
	v_mov_b32_e32 v40, v42
	s_waitcnt vmcnt(2)
	v_lshlrev_b32_e32 v36, 16, v38
	v_and_b32_e32 v34, 0xffff0000, v38
	v_lshlrev_b32_e32 v32, 16, v39
	s_waitcnt vmcnt(1)
	v_mov_b32_e32 v41, v4
	v_mov_b32_e32 v4, v43
	s_waitcnt vmcnt(0)
	v_lshlrev_b32_e32 v37, 16, v30
	v_and_b32_e32 v35, 0xffff0000, v30
	v_and_b32_e32 v30, 0xffff0000, v39
	v_pk_mul_f32 v[38:39], v[4:5], v[4:5]
	v_lshlrev_b32_e32 v33, 16, v31
	v_pk_fma_f32 v[42:43], v[40:41], v[40:41], v[38:39]
	v_mov_b32_e32 v38, v44
	v_mov_b32_e32 v39, v6
	v_pk_fma_f32 v[42:43], v[38:39], v[38:39], v[42:43]
	v_mov_b32_e32 v6, v45
	v_pk_fma_f32 v[42:43], v[6:7], v[6:7], v[42:43]
	v_and_b32_e32 v31, 0xffff0000, v31
	v_add_f32_e32 v9, v9, v42
	v_add_f32_e32 v42, v9, v43
	v_and_b32_e32 v9, 64, v198
	v_add_u32_e32 v44, 64, v9
	v_xor_b32_e32 v9, 1, v198
	v_cmp_lt_i32_e32 vcc, v9, v44
	s_nop 1
	v_cndmask_b32_e32 v9, v198, v9, vcc
	v_lshlrev_b32_e32 v9, 2, v9
	ds_bpermute_b32 v43, v9, v42
	s_waitcnt lgkmcnt(0)
	v_add_f32_e32 v43, v42, v43
	v_xor_b32_e32 v42, 2, v198
	v_cmp_lt_i32_e32 vcc, v42, v44
	s_nop 1
	v_cndmask_b32_e32 v42, v198, v42, vcc
	v_lshlrev_b32_e32 v42, 2, v42
	ds_bpermute_b32 v45, v42, v43
	s_waitcnt lgkmcnt(0)
	v_add_f32_e32 v45, v43, v45
	v_xor_b32_e32 v43, 4, v198
	v_cmp_lt_i32_e32 vcc, v43, v44
	s_nop 1
	v_cndmask_b32_e32 v43, v198, v43, vcc
	v_lshlrev_b32_e32 v43, 2, v43
	ds_bpermute_b32 v46, v43, v45
	s_waitcnt lgkmcnt(0)
	v_add_f32_e32 v45, v45, v46
	v_xor_b32_e32 v46, 8, v198
	v_cmp_lt_i32_e32 vcc, v46, v44
	s_nop 1
	v_cndmask_b32_e32 v46, v198, v46, vcc
	v_lshlrev_b32_e32 v53, 2, v46
	ds_bpermute_b32 v46, v53, v45
	s_waitcnt lgkmcnt(0)
	v_add_f32_e32 v45, v45, v46
	v_xor_b32_e32 v46, 16, v198
	v_cmp_lt_i32_e32 vcc, v46, v44
	s_nop 1
	v_cndmask_b32_e32 v46, v198, v46, vcc
	v_lshlrev_b32_e32 v56, 2, v46
	ds_bpermute_b32 v46, v56, v45
	s_waitcnt lgkmcnt(0)
	v_add_f32_e32 v45, v45, v46
	v_xor_b32_e32 v46, 32, v198
	v_cmp_lt_i32_e32 vcc, v46, v44
	s_nop 1
	v_cndmask_b32_e32 v44, v198, v46, vcc
	v_lshlrev_b32_e32 v57, 2, v44
	ds_bpermute_b32 v44, v57, v45
	s_waitcnt lgkmcnt(0)
	v_add_f32_e32 v44, v45, v44
	v_fmamk_f32 v44, v44, 0x3a800000, v193
	v_cmp_gt_f32_e32 vcc, s92, v44
	v_mul_f32_e32 v45, 0x4b800000, v44
	s_nop 0
	v_cndmask_b32_e32 v44, v44, v45, vcc
	v_rsq_f32_e32 v44, v44
	s_nop 0
	v_mul_f32_e32 v45, 0x45800000, v44
	v_cndmask_b32_e32 v52, v44, v45, vcc
	s_nop 1
	v_mov_b32_e32 v44, v60
	v_mov_b32_e32 v45, v61
	v_mov_b32_e32 v46, v62
	v_mov_b32_e32 v47, v63
	s_nop 1
	v_mov_b32_e32 v48, v64
	v_mov_b32_e32 v49, v65
	v_mov_b32_e32 v50, v66
	v_mov_b32_e32 v51, v67
	v_pk_mul_f32 v[0:1], v[0:1], v[52:53] op_sel_hi:[1,0]
	v_pk_mul_f32 v[28:29], v[28:29], v[52:53] op_sel_hi:[1,0]
	v_pk_mul_f32 v[6:7], v[6:7], v[52:53] op_sel_hi:[1,0]
	s_waitcnt vmcnt(1)
	v_mov_b32_e32 v54, v44
	s_waitcnt vmcnt(0)
;   __device__ __forceinline__ bf16* h() const { unsigned o_ = (unsigned)(OFF_h); asm volatile("" : "+s"(o_)); return (bf16*)(ws + o_); }
;   __device__ __forceinline__ bf16* xn() const { unsigned o_ = (unsigned)(OFF_xn); asm volatile("" : "+s"(o_)); return (bf16*)(ws + o_); }
;   __device__ __forceinline__ bf16* y() const { unsigned o_ = (unsigned)(OFF_y); asm volatile("" : "+s"(o_)); return (bf16*)(ws + o_); }
; __device__ __forceinline__ unsigned pk2(float a, float b) { unsigned r; asm("v_cvt_pk_bf16_f32 %0, %1, %2" : "=v"(r) : "v"(a), "v"(b)); return r; }
; __device__ __forceinline__ void write_xn_row(bf16* dst, const float4 (&v)[4], float rs, const float* g, int lane, bool valid) {
; #pragma unroll
;   for (int i = 0; i < 4; ++i) {
;     const int c = i * 256 + lane * 4;
;     float4 gg = *(const float4*)(g + c);
;     uint2 o;
;     if (valid) { o.x = pk2(v[i].x * rs * gg.x, v[i].y * rs * gg.y); o.y = pk2(v[i].z * rs * gg.z, v[i].w * rs * gg.w); }
;     else { o.x = 0u; o.y = 0u; }
;     *(uint2*)(dst + c) = o;
;   }
; }
; __device__ void phase_norm(const P& p, const float* gpost, const float* gnext, bool last, int rowbeg, int rowend) {
;     ...
;     for (int i = 0; i < 4; ++i) {
;       float4 gg = *(const float4*)(gpost + i * 256 + lane * 4);
;       hv[i].x += m[i].x * rs * gg.x; hv[i].y += m[i].y * rs * gg.y; hv[i].z += m[i].z * rs * gg.z; hv[i].w += m[i].w * rs * gg.w;
;       ss2 += hv[i].x * hv[i].x + hv[i].y * hv[i].y + hv[i].z * hv[i].z + hv[i].w * hv[i].w;
;     }
;     if (last) {
;       if (t >= 128) {
; #pragma unroll
;         for (int i = 0; i < 4; ++i) *(float4*)(p.out + ((size_t)b * SEQ + (t - 128)) * D + i * 256 + lane * 4) = hv[i];
;       }
;     } else {
; #pragma unroll
;       for (int i = 0; i < 4; ++i) { uint2 hb_; hb_.x = pk2(hv[i].x, hv[i].y); hb_.y = pk2(hv[i].z, hv[i].w); *(uint2*)(p.h() + (size_t)row * D + i * 256 + lane * 4) = hb_; }
;       ss2 = wave_sum(ss2);
;       const float rs2 = rsqrtf(ss2 * (1.f / D) + EPS);
;       write_xn_row(p.xn() + (size_t)row * D, hv, rs2, gnext, lane, true);
;     }
	v_mov_b32_e32 v55, v48
	v_mov_b32_e32 v48, v45
	v_pk_fma_f32 v[22:23], v[48:49], v[0:1], v[22:23]
	v_pk_mul_f32 v[0:1], v[26:27], v[52:53] op_sel_hi:[1,0]
	v_mov_b32_e32 v26, v46
	v_mov_b32_e32 v27, v50
	v_pk_fma_f32 v[24:25], v[54:55], v[28:29], v[24:25]
	v_pk_fma_f32 v[20:21], v[26:27], v[0:1], v[20:21]
	v_mov_b32_e32 v50, v47
	s_nop 1
	v_mov_b32_e32 v26, v68
	v_mov_b32_e32 v27, v69
	v_mov_b32_e32 v28, v70
	v_mov_b32_e32 v29, v71
	s_nop 1
	v_mov_b32_e32 v44, v72
	v_mov_b32_e32 v45, v73
	v_mov_b32_e32 v46, v74
	v_mov_b32_e32 v47, v75
	v_pk_mul_f32 v[0:1], v[2:3], v[52:53] op_sel_hi:[1,0]
	s_add_u32 s4, s76, s4
	v_pk_fma_f32 v[18:19], v[50:51], v[0:1], v[18:19]
	v_pk_mul_f32 v[0:1], v[40:41], v[52:53] op_sel_hi:[1,0]
	s_addc_u32 s5, s77, 0
	s_waitcnt vmcnt(1)
	v_mov_b32_e32 v2, v26
	s_waitcnt vmcnt(0)
	v_mov_b32_e32 v3, v44
	v_pk_fma_f32 v[0:1], v[2:3], v[0:1], v[36:37]
	v_pk_mul_f32 v[2:3], v[4:5], v[52:53] op_sel_hi:[1,0]
	v_mov_b32_e32 v44, v27
	v_pk_mul_f32 v[4:5], v[38:39], v[52:53] op_sel_hi:[1,0]
	v_mov_b32_e32 v26, v28
	v_mov_b32_e32 v27, v46
	v_pk_fma_f32 v[2:3], v[44:45], v[2:3], v[34:35]
	v_pk_fma_f32 v[4:5], v[4:5], v[26:27], v[32:33]
	v_pk_mul_f32 v[26:27], v[22:23], v[22:23]
	v_mov_b32_e32 v46, v29
	v_pk_fma_f32 v[26:27], v[24:25], v[24:25], v[26:27]
	v_pk_mul_f32 v[28:29], v[2:3], v[2:3]
	v_pk_fma_f32 v[26:27], v[20:21], v[20:21], v[26:27]
	v_pk_fma_f32 v[28:29], v[0:1], v[0:1], v[28:29]
	v_pk_fma_f32 v[6:7], v[6:7], v[46:47], v[30:31]
	v_pk_fma_f32 v[26:27], v[18:19], v[18:19], v[26:27]
	v_pk_fma_f32 v[28:29], v[4:5], v[4:5], v[28:29]
	v_add_f32_e32 v26, v26, v27
	v_pk_fma_f32 v[28:29], v[6:7], v[6:7], v[28:29]
	v_cvt_pk_bf16_f32 v27, v20, v18
	s_nop 0
	v_add_f32_e32 v26, v28, v26
	v_add_f32_e32 v30, v26, v29
	v_lshl_add_u64 v[28:29], s[4:5], 0, v[14:15]
	s_mov_b32 s4, s97
	v_cvt_pk_bf16_f32 v26, v24, v22
	global_store_dwordx2 v[28:29], v[26:27], off
	s_add_u32 s4, s76, s4
	s_addc_u32 s5, s77, 0
	v_lshl_add_u64 v[28:29], s[4:5], 0, v[14:15]
	s_mov_b32 s4, s97
	v_cvt_pk_bf16_f32 v26, v25, v23
	v_cvt_pk_bf16_f32 v27, v21, v19
	global_store_dwordx2 v[28:29], v[26:27], off offset:512
	s_add_u32 s4, s76, s4
	s_addc_u32 s5, s77, 0
	ds_bpermute_b32 v9, v9, v30
	v_lshl_add_u64 v[28:29], s[4:5], 0, v[14:15]
	s_mov_b32 s4, s97
	v_cvt_pk_bf16_f32 v26, v0, v2
	v_cvt_pk_bf16_f32 v27, v4, v6
	global_store_dwordx2 v[28:29], v[26:27], off offset:1024
	s_add_u32 s4, s76, s4
	s_addc_u32 s5, s77, 0
	v_cvt_pk_bf16_f32 v26, v1, v3
	v_lshl_add_u64 v[28:29], s[4:5], 0, v[14:15]
	s_waitcnt lgkmcnt(0)
	v_add_f32_e32 v9, v30, v9
	v_cvt_pk_bf16_f32 v27, v5, v7
	global_store_dwordx2 v[28:29], v[26:27], off offset:1536
	ds_bpermute_b32 v26, v42, v9
	s_mov_b32 s4, 0x4100000
	s_add_u32 s4, s76, s4
	s_addc_u32 s5, s77, 0
	s_waitcnt lgkmcnt(0)
	v_add_f32_e32 v9, v9, v26
	ds_bpermute_b32 v26, v43, v9
	v_lshl_add_u64 v[30:31], s[4:5], 0, v[14:15]
	v_lshl_add_u64 v[14:15], v[14:15], 0, s[12:13]
	s_waitcnt lgkmcnt(0)
	v_add_f32_e32 v9, v9, v26
	ds_bpermute_b32 v26, v53, v9
	s_waitcnt lgkmcnt(0)
	v_add_f32_e32 v9, v9, v26
	ds_bpermute_b32 v26, v56, v9
	s_waitcnt lgkmcnt(0)
	v_add_f32_e32 v9, v9, v26
	ds_bpermute_b32 v26, v57, v9
	s_waitcnt lgkmcnt(0)
	v_add_f32_e32 v9, v9, v26
	v_fmamk_f32 v9, v9, 0x3a800000, v193
	v_cmp_gt_f32_e32 vcc, s92, v9
	v_mul_f32_e32 v26, 0x4b800000, v9
	s_nop 0
	v_cndmask_b32_e32 v9, v9, v26, vcc
	v_rsq_f32_e32 v9, v9
	s_nop 0
	v_mul_f32_e32 v26, 0x45800000, v9
	v_cndmask_b32_e32 v9, v9, v26, vcc
	s_nop 1
	v_mov_b32_e32 v26, v76
	v_mov_b32_e32 v27, v77
	v_mov_b32_e32 v28, v78
	v_mov_b32_e32 v29, v79
	v_mul_f32_e32 v24, v24, v9
	v_mul_f32_e32 v22, v22, v9
	v_mul_f32_e32 v20, v20, v9
	v_mul_f32_e32 v18, v18, v9
	v_mul_f32_e32 v19, v19, v9
	v_mul_f32_e32 v0, v0, v9
	v_mul_f32_e32 v2, v2, v9
	v_cmp_lt_i32_e32 vcc, s6, v8
	s_or_b64 s[2:3], vcc, s[2:3]
	s_nop 0
	v_mul_f32_e32 v24, v26, v24
	v_mul_f32_e32 v22, v27, v22
	v_cvt_pk_bf16_f32 v26, v24, v22
	v_mul_f32_e32 v20, v28, v20
	v_mul_f32_e32 v18, v29, v18
	v_cvt_pk_bf16_f32 v27, v20, v18
	global_store_dwordx2 v[30:31], v[26:27], off
	s_nop 1
	v_mov_b32_e32 v26, v80
	v_mov_b32_e32 v27, v81
	v_mov_b32_e32 v28, v82
	v_mov_b32_e32 v29, v83
	v_mul_f32_e32 v18, v25, v9
	v_mul_f32_e32 v20, v23, v9
	s_nop 0
	v_mul_f32_e32 v18, v18, v26
	v_mul_f32_e32 v20, v20, v27
	v_cvt_pk_bf16_f32 v18, v18, v20
	v_mul_f32_e32 v20, v21, v9
	v_mul_f32_e32 v19, v29, v19
	v_mul_f32_e32 v20, v20, v28
	v_cvt_pk_bf16_f32 v19, v20, v19
	global_store_dwordx2 v[30:31], v[18:19], off offset:512
	s_nop 1
	v_mov_b32_e32 v18, v84
	v_mov_b32_e32 v19, v85
	v_mov_b32_e32 v20, v86
	v_mov_b32_e32 v21, v87
	s_nop 0
	v_mul_f32_e32 v0, v0, v18
	v_mul_f32_e32 v2, v2, v19
	v_cvt_pk_bf16_f32 v18, v0, v2
	v_mul_f32_e32 v0, v4, v9
	v_mul_f32_e32 v2, v6, v9
	v_mul_f32_e32 v0, v0, v20
	v_mul_f32_e32 v2, v2, v21
	v_cvt_pk_bf16_f32 v19, v0, v2
	global_store_dwordx2 v[30:31], v[18:19], off offset:1024
	s_nop 1
	v_mov_b32_e32 v18, v88
	v_mov_b32_e32 v19, v89
	v_mov_b32_e32 v20, v90
	v_mov_b32_e32 v21, v91
	v_mul_f32_e32 v0, v1, v9
	v_mul_f32_e32 v1, v3, v9
	v_mul_f32_e32 v2, v7, v9
	s_nop 0
	v_mul_f32_e32 v0, v0, v18
	v_mul_f32_e32 v1, v1, v19
	v_cvt_pk_bf16_f32 v0, v0, v1
	v_mul_f32_e32 v1, v5, v9
	v_mul_f32_e32 v1, v1, v20
	v_mul_f32_e32 v2, v2, v21
	v_cvt_pk_bf16_f32 v1, v1, v2
	global_store_dwordx2 v[30:31], v[0:1], off offset:1536
	s_andn2_b64 exec, exec, s[2:3]
	s_cbranch_execnz .LBB0_929

;   __device__ __forceinline__ bf16* h() const { unsigned o_ = (unsigned)(OFF_h); asm volatile("" : "+s"(o_)); return (bf16*)(ws + o_); }
;   __device__ __forceinline__ bf16* y() const { unsigned o_ = (unsigned)(OFF_y); asm volatile("" : "+s"(o_)); return (bf16*)(ws + o_); }
;   __device__ __forceinline__ float* tmp() const { unsigned o_ = (unsigned)(OFF_U + (size_t)100663296); asm volatile("" : "+s"(o_)); return (float*)(ws + o_); }
; __device__ __forceinline__ float lo16(unsigned v) { return __uint_as_float(v << 16); }
; __device__ __forceinline__ float hi16(unsigned v) { return __uint_as_float(v & 0xffff0000u); }
; __device__ void phase_norm(const P& p, const float* gpost, const float* gnext, bool last, int rowbeg, int rowend) {
;     ...
;   for (int row = rowbeg + gw; row < rowend; row += nw) {
;     const int b = row / RB, t = row % RB + PADB;
;     float4 m[4], hv[4];
;     float ss = 0.f;
; #pragma unroll
;     for (int i = 0; i < 4; ++i) {
;       m[i] = *(const float4*)(p.tmp() + (size_t)row * D + i * 256 + lane * 4);
;       { const uint2 hb_ = *(const uint2*)(p.h() + (size_t)row * D + i * 256 + lane * 4); hv[i] = make_float4(lo16(hb_.x), hi16(hb_.x), lo16(hb_.y), hi16(hb_.y)); }
;       ss += m[i].x * m[i].x + m[i].y * m[i].y + m[i].z * m[i].z + m[i].w * m[i].w;
;     }
;     ss = wave_sum(ss);
;     const float rs = rsqrtf(ss * (1.f / D) + EPS);
;     float ss2 = 0.f;
; #pragma unroll
;     for (int i = 0; i < 4; ++i) {
;       float4 gg = *(const float4*)(gpost + i * 256 + lane * 4);
;       hv[i].x += m[i].x * rs * gg.x; hv[i].y += m[i].y * rs * gg.y; hv[i].z += m[i].z * rs * gg.z; hv[i].w += m[i].w * rs * gg.w;
;       ss2 += hv[i].x * hv[i].x + hv[i].y * hv[i].y + hv[i].z * hv[i].z + hv[i].w * hv[i].w;
;     }
.LBB0_1294:
	s_mov_b32 s6, 0xc180000
	v_ashrrev_i32_e32 v21, 31, v20
	s_add_u32 s6, s76, s6
	s_addc_u32 s7, s77, 0
	v_lshlrev_b64 v[12:13], 12, v[20:21]
	v_lshl_add_u64 v[0:1], s[6:7], 0, v[12:13]
	v_lshlrev_b32_e32 v28, 2, v22
	v_mov_b32_e32 v29, v139
	v_lshl_add_u64 v[0:1], v[0:1], 0, v[28:29]
	s_mov_b32 s6, s97
	global_load_dwordx4 v[0:3], v[0:1], off
	s_add_u32 s6, s76, s6
	s_addc_u32 s7, s77, 0
	v_lshlrev_b64 v[30:31], 11, v[20:21]
	v_lshl_add_u64 v[4:5], s[6:7], 0, v[30:31]
	v_lshlrev_b32_e32 v138, 1, v22
	v_lshl_add_u64 v[4:5], v[4:5], 0, v[138:139]
	global_load_dwordx2 v[4:5], v[4:5], off
	global_load_dwordx4 v[60:63], v[24:25], off
	global_load_dwordx4 v[64:67], v[24:25], off offset:1024
	global_load_dwordx4 v[68:71], v[24:25], off offset:2048
	global_load_dwordx4 v[72:75], v[24:25], off offset:3072
	global_load_dwordx4 v[76:79], v[26:27], off
	global_load_dwordx4 v[80:83], v[26:27], off offset:1024
	global_load_dwordx4 v[84:87], v[26:27], off offset:2048
	global_load_dwordx4 v[88:91], v[26:27], off offset:3072
	s_mov_b32 s6, 0xc180000
	s_add_u32 s6, s76, s6
	s_addc_u32 s7, s77, 0
	s_waitcnt vmcnt(9)
	v_mov_b32_e32 v10, v1
	v_mov_b32_e32 v14, v3
	s_waitcnt vmcnt(8)
	v_lshlrev_b32_e32 v18, 16, v4
	v_and_b32_e32 v19, 0xffff0000, v4
	v_lshlrev_b32_e32 v16, 16, v5
	v_and_b32_e32 v17, 0xffff0000, v5
	v_lshl_add_u64 v[4:5], s[6:7], 0, v[12:13]
	v_lshl_add_u64 v[4:5], v[4:5], 0, v[28:29]
	s_mov_b32 s6, s97
	global_load_dwordx4 v[4:7], v[4:5], off offset:1024
	s_add_u32 s6, s76, s6
	s_addc_u32 s7, s77, 0
	v_lshl_add_u64 v[8:9], s[6:7], 0, v[30:31]
	v_lshl_add_u64 v[8:9], v[8:9], 0, v[138:139]
	global_load_dwordx2 v[8:9], v[8:9], off offset:512
	s_mov_b32 s6, 0xc180000
	s_add_u32 s6, s76, s6
	s_addc_u32 s7, s77, 0
	s_waitcnt vmcnt(1)
	v_mov_b32_e32 v11, v5
	v_pk_mul_f32 v[10:11], v[10:11], v[10:11]
	v_mov_b32_e32 v15, v7
	s_waitcnt vmcnt(0)
	v_lshlrev_b32_e32 v38, 16, v8
	v_and_b32_e32 v39, 0xffff0000, v8
	v_lshlrev_b32_e32 v36, 16, v9
	v_and_b32_e32 v37, 0xffff0000, v9
	v_mov_b32_e32 v8, v0
	v_mov_b32_e32 v9, v4
	v_pk_fma_f32 v[8:9], v[8:9], v[8:9], v[10:11]
	v_mov_b32_e32 v10, v2
	v_mov_b32_e32 v11, v6
	v_pk_fma_f32 v[8:9], v[10:11], v[10:11], v[8:9]
	s_nop 0
	v_pk_fma_f32 v[40:41], v[14:15], v[14:15], v[8:9]
	v_lshl_add_u64 v[8:9], s[6:7], 0, v[12:13]
	v_lshl_add_u64 v[8:9], v[8:9], 0, v[28:29]
	s_mov_b32 s6, s97
	global_load_dwordx4 v[8:11], v[8:9], off offset:2048
	s_add_u32 s6, s76, s6
	s_addc_u32 s7, s77, 0
	v_lshl_add_u64 v[14:15], s[6:7], 0, v[30:31]
	v_lshl_add_u64 v[14:15], v[14:15], 0, v[138:139]
	global_load_dwordx2 v[14:15], v[14:15], off offset:1024
	s_mov_b32 s6, 0xc180000
	s_add_u32 s6, s76, s6
	s_addc_u32 s7, s77, 0
	v_lshl_add_u64 v[12:13], s[6:7], 0, v[12:13]
	v_lshl_add_u64 v[12:13], v[12:13], 0, v[28:29]
	v_add_f32_e32 v21, v40, v41
	s_mov_b32 s6, s97
	s_waitcnt vmcnt(1)
	v_mov_b32_e32 v48, v9
	v_mov_b32_e32 v46, v8
	v_mov_b32_e32 v50, v11
	s_waitcnt vmcnt(0)
	v_lshlrev_b32_e32 v44, 16, v14
	v_and_b32_e32 v45, 0xffff0000, v14
	v_lshlrev_b32_e32 v42, 16, v15
	v_and_b32_e32 v43, 0xffff0000, v15
	global_load_dwordx4 v[12:15], v[12:13], off offset:3072
	s_add_u32 s6, s76, s6
	s_addc_u32 s7, s77, 0
	v_lshl_add_u64 v[32:33], s[6:7], 0, v[30:31]
	v_lshl_add_u64 v[32:33], v[32:33], 0, v[138:139]
	global_load_dwordx2 v[32:33], v[32:33], off offset:1536
	s_mov_b64 s[6:7], -1
	s_waitcnt vmcnt(1)
	v_mov_b32_e32 v49, v13
	v_mov_b32_e32 v47, v12
	v_pk_mul_f32 v[48:49], v[48:49], v[48:49]
	v_mov_b32_e32 v51, v15
	v_pk_fma_f32 v[46:47], v[46:47], v[46:47], v[48:49]
	v_mov_b32_e32 v48, v10
	v_mov_b32_e32 v49, v14
	v_pk_fma_f32 v[46:47], v[48:49], v[48:49], v[46:47]
	s_waitcnt vmcnt(0)
	v_lshlrev_b32_e32 v34, 16, v32
	v_pk_fma_f32 v[46:47], v[50:51], v[50:51], v[46:47]
	v_and_b32_e32 v35, 0xffff0000, v32
	v_add_f32_e32 v21, v21, v46
	v_add_f32_e32 v23, v21, v47
	v_and_b32_e32 v21, 64, v198
	v_add_u32_e32 v40, 64, v21
	v_xor_b32_e32 v21, 1, v198
	v_cmp_lt_i32_e32 vcc, v21, v40
	v_lshlrev_b32_e32 v32, 16, v33
	v_and_b32_e32 v33, 0xffff0000, v33
	v_cndmask_b32_e32 v21, v198, v21, vcc
	v_lshlrev_b32_e32 v21, 2, v21
	ds_bpermute_b32 v29, v21, v23
	s_waitcnt lgkmcnt(0)
	v_add_f32_e32 v29, v23, v29
	v_xor_b32_e32 v23, 2, v198
	v_cmp_lt_i32_e32 vcc, v23, v40
	s_nop 1
	v_cndmask_b32_e32 v23, v198, v23, vcc
	v_lshlrev_b32_e32 v23, 2, v23
	ds_bpermute_b32 v41, v23, v29
	s_waitcnt lgkmcnt(0)
	v_add_f32_e32 v41, v29, v41
	v_xor_b32_e32 v29, 4, v198
	v_cmp_lt_i32_e32 vcc, v29, v40
	s_nop 1
	v_cndmask_b32_e32 v29, v198, v29, vcc
	v_lshlrev_b32_e32 v29, 2, v29
	ds_bpermute_b32 v46, v29, v41
	s_waitcnt lgkmcnt(0)
	v_add_f32_e32 v46, v41, v46
	v_xor_b32_e32 v41, 8, v198
	v_cmp_lt_i32_e32 vcc, v41, v40
	s_nop 1
	v_cndmask_b32_e32 v41, v198, v41, vcc
	v_lshlrev_b32_e32 v41, 2, v41
	ds_bpermute_b32 v47, v41, v46
	s_waitcnt lgkmcnt(0)
	v_add_f32_e32 v47, v46, v47
	v_xor_b32_e32 v46, 16, v198
	v_cmp_lt_i32_e32 vcc, v46, v40
	s_nop 1
	v_cndmask_b32_e32 v46, v198, v46, vcc
	v_lshlrev_b32_e32 v46, 2, v46
	ds_bpermute_b32 v48, v46, v47
	s_waitcnt lgkmcnt(0)
	v_add_f32_e32 v48, v47, v48
	v_xor_b32_e32 v47, 32, v198
	v_cmp_lt_i32_e32 vcc, v47, v40
	s_nop 1
	v_cndmask_b32_e32 v40, v198, v47, vcc
	v_lshlrev_b32_e32 v47, 2, v40
	ds_bpermute_b32 v40, v47, v48
	s_waitcnt lgkmcnt(0)
	v_add_f32_e32 v40, v48, v40
	v_fmamk_f32 v40, v40, 0x3a800000, v193
	v_cmp_gt_f32_e32 vcc, s92, v40
	v_mul_f32_e32 v48, 0x4b800000, v40
	s_nop 0
	v_cndmask_b32_e32 v40, v40, v48, vcc
	v_rsq_f32_e32 v40, v40
	s_nop 0
	v_mul_f32_e32 v48, 0x45800000, v40
	v_cndmask_b32_e32 v40, v40, v48, vcc
	s_nop 1
	v_mov_b32_e32 v48, v60
	v_mov_b32_e32 v49, v61
	v_mov_b32_e32 v50, v62
	v_mov_b32_e32 v51, v63
	v_pk_mul_f32 v[0:1], v[0:1], v[40:41] op_sel_hi:[1,0]
	v_pk_mul_f32 v[2:3], v[2:3], v[40:41] op_sel_hi:[1,0]
	v_pk_mul_f32 v[4:5], v[4:5], v[40:41] op_sel_hi:[1,0]
	v_pk_mul_f32 v[6:7], v[6:7], v[40:41] op_sel_hi:[1,0]
	v_pk_mul_f32 v[8:9], v[8:9], v[40:41] op_sel_hi:[1,0]
	v_pk_mul_f32 v[10:11], v[10:11], v[40:41] op_sel_hi:[1,0]
	v_pk_mul_f32 v[12:13], v[12:13], v[40:41] op_sel_hi:[1,0]
	v_pk_mul_f32 v[14:15], v[14:15], v[40:41] op_sel_hi:[1,0]
	s_and_b64 vcc, exec, s[2:3]
	s_waitcnt vmcnt(0)
	v_pk_fma_f32 v[0:1], v[48:49], v[0:1], v[18:19]
	v_pk_fma_f32 v[2:3], v[50:51], v[2:3], v[16:17]
	s_nop 1
	v_mov_b32_e32 v16, v64
	v_mov_b32_e32 v17, v65
	v_mov_b32_e32 v18, v66
	v_mov_b32_e32 v19, v67
	s_waitcnt vmcnt(0)
	v_pk_fma_f32 v[4:5], v[16:17], v[4:5], v[38:39]
	v_pk_fma_f32 v[6:7], v[18:19], v[6:7], v[36:37]
	s_nop 1
	v_mov_b32_e32 v16, v68
	v_mov_b32_e32 v17, v69
	v_mov_b32_e32 v18, v70
	v_mov_b32_e32 v19, v71
	s_waitcnt vmcnt(0)
	v_pk_fma_f32 v[8:9], v[16:17], v[8:9], v[44:45]
	v_pk_fma_f32 v[10:11], v[10:11], v[18:19], v[42:43]
	s_nop 1
	v_mov_b32_e32 v16, v72
	v_mov_b32_e32 v17, v73
	v_mov_b32_e32 v18, v74
	v_mov_b32_e32 v19, v75
	s_waitcnt vmcnt(0)
	v_pk_fma_f32 v[12:13], v[12:13], v[16:17], v[34:35]
	v_pk_fma_f32 v[14:15], v[14:15], v[18:19], v[32:33]
	s_cbranch_vccnz .LBB0_1296
;   __device__ __forceinline__ bf16* h() const { unsigned o_ = (unsigned)(OFF_h); asm volatile("" : "+s"(o_)); return (bf16*)(ws + o_); }
;   __device__ __forceinline__ bf16* xn() const { unsigned o_ = (unsigned)(OFF_xn); asm volatile("" : "+s"(o_)); return (bf16*)(ws + o_); }
;   __device__ __forceinline__ bf16* y() const { unsigned o_ = (unsigned)(OFF_y); asm volatile("" : "+s"(o_)); return (bf16*)(ws + o_); }
; __device__ __forceinline__ unsigned pk2(float a, float b) { unsigned r; asm("v_cvt_pk_bf16_f32 %0, %1, %2" : "=v"(r) : "v"(a), "v"(b)); return r; }
; __device__ __forceinline__ void write_xn_row(bf16* dst, const float4 (&v)[4], float rs, const float* g, int lane, bool valid) {
; #pragma unroll
;   for (int i = 0; i < 4; ++i) {
;     const int c = i * 256 + lane * 4;
;     float4 gg = *(const float4*)(g + c);
;     uint2 o;
;     if (valid) { o.x = pk2(v[i].x * rs * gg.x, v[i].y * rs * gg.y); o.y = pk2(v[i].z * rs * gg.z, v[i].w * rs * gg.w); }
;     else { o.x = 0u; o.y = 0u; }
;     *(uint2*)(dst + c) = o;
;   }
; }
; __device__ void phase_norm(const P& p, const float* gpost, const float* gnext, bool last, int rowbeg, int rowend) {
;     ...
; #pragma unroll
;       for (int i = 0; i < 4; ++i) { uint2 hb_; hb_.x = pk2(hv[i].x, hv[i].y); hb_.y = pk2(hv[i].z, hv[i].w); *(uint2*)(p.h() + (size_t)row * D + i * 256 + lane * 4) = hb_; }
;       ss2 = wave_sum(ss2);
;       const float rs2 = rsqrtf(ss2 * (1.f / D) + EPS);
;       write_xn_row(p.xn() + (size_t)row * D, hv, rs2, gnext, lane, true);
;     }
	v_mov_b32_e32 v18, v1
	v_mov_b32_e32 v19, v5
	v_mov_b32_e32 v16, v0
	v_mov_b32_e32 v17, v4
	v_pk_mul_f32 v[18:19], v[18:19], v[18:19]
	v_mov_b32_e32 v32, v9
	v_pk_fma_f32 v[16:17], v[16:17], v[16:17], v[18:19]
	v_mov_b32_e32 v18, v2
	v_mov_b32_e32 v19, v6
	v_pk_fma_f32 v[16:17], v[18:19], v[18:19], v[16:17]
	v_mov_b32_e32 v18, v3
	v_mov_b32_e32 v19, v7
	v_mov_b32_e32 v33, v13
	v_pk_fma_f32 v[16:17], v[18:19], v[18:19], v[16:17]
	v_mov_b32_e32 v18, v8
	v_mov_b32_e32 v19, v12
	v_pk_mul_f32 v[32:33], v[32:33], v[32:33]
	s_mov_b32 s6, s97
	v_pk_fma_f32 v[18:19], v[18:19], v[18:19], v[32:33]
	v_mov_b32_e32 v32, v10
	v_mov_b32_e32 v33, v14
	v_pk_fma_f32 v[18:19], v[32:33], v[32:33], v[18:19]
	v_mov_b32_e32 v32, v11
	v_mov_b32_e32 v33, v15
	v_pk_fma_f32 v[18:19], v[32:33], v[32:33], v[18:19]
	v_add_f32_e32 v16, v16, v17
	s_add_u32 s6, s76, s6
	v_add_f32_e32 v16, v18, v16
	s_addc_u32 s7, s77, 0
	v_add_f32_e32 v32, v16, v19
	v_lshl_add_u64 v[18:19], s[6:7], 0, v[30:31]
	v_lshl_add_u64 v[18:19], v[18:19], 0, v[138:139]
	s_mov_b32 s6, s97
	v_cvt_pk_bf16_f32 v16, v0, v1
	v_cvt_pk_bf16_f32 v17, v2, v3
	global_store_dwordx2 v[18:19], v[16:17], off
	s_add_u32 s6, s76, s6
	s_addc_u32 s7, s77, 0
	v_lshl_add_u64 v[18:19], s[6:7], 0, v[30:31]
	v_lshl_add_u64 v[18:19], v[18:19], 0, v[138:139]
	s_mov_b32 s6, s97
	v_cvt_pk_bf16_f32 v16, v4, v5
	v_cvt_pk_bf16_f32 v17, v6, v7
	global_store_dwordx2 v[18:19], v[16:17], off offset:512
	s_add_u32 s6, s76, s6
	s_addc_u32 s7, s77, 0
	v_lshl_add_u64 v[18:19], s[6:7], 0, v[30:31]
	v_lshl_add_u64 v[18:19], v[18:19], 0, v[138:139]
	s_mov_b32 s6, s97
	v_cvt_pk_bf16_f32 v16, v8, v9
	v_cvt_pk_bf16_f32 v17, v10, v11
	global_store_dwordx2 v[18:19], v[16:17], off offset:1024
	s_add_u32 s6, s76, s6
	s_addc_u32 s7, s77, 0
	v_lshl_add_u64 v[18:19], s[6:7], 0, v[30:31]
	v_cvt_pk_bf16_f32 v16, v12, v13
	v_lshl_add_u64 v[18:19], v[18:19], 0, v[138:139]
	v_cvt_pk_bf16_f32 v17, v14, v15
	global_store_dwordx2 v[18:19], v[16:17], off offset:1536
	ds_bpermute_b32 v16, v21, v32
	s_mov_b32 s6, 0x4100000
	s_add_u32 s6, s76, s6
	s_addc_u32 s7, s77, 0
	s_waitcnt lgkmcnt(0)
	v_add_f32_e32 v16, v32, v16
	ds_bpermute_b32 v17, v23, v16
	v_lshl_add_u64 v[30:31], s[6:7], 0, v[30:31]
	v_lshl_add_u64 v[30:31], v[30:31], 0, v[138:139]
	s_mov_b64 s[6:7], 0
	s_waitcnt lgkmcnt(0)
	v_add_f32_e32 v16, v16, v17
	ds_bpermute_b32 v17, v29, v16
	s_waitcnt lgkmcnt(0)
	v_add_f32_e32 v16, v16, v17
	ds_bpermute_b32 v17, v41, v16
	s_waitcnt lgkmcnt(0)
	v_add_f32_e32 v16, v16, v17
	ds_bpermute_b32 v17, v46, v16
	s_waitcnt lgkmcnt(0)
	v_add_f32_e32 v16, v16, v17
	ds_bpermute_b32 v17, v47, v16
	s_waitcnt lgkmcnt(0)
	v_add_f32_e32 v16, v16, v17
	v_fmamk_f32 v16, v16, 0x3a800000, v193
	v_cmp_gt_f32_e32 vcc, s92, v16
	v_mul_f32_e32 v17, 0x4b800000, v16
	s_nop 0
	v_cndmask_b32_e32 v16, v16, v17, vcc
	v_rsq_f32_e32 v16, v16
	s_nop 0
	v_mul_f32_e32 v17, 0x45800000, v16
	v_cndmask_b32_e32 v21, v16, v17, vcc
	s_nop 1
	v_mov_b32_e32 v16, v76
	v_mov_b32_e32 v17, v77
	v_mov_b32_e32 v18, v78
	v_mov_b32_e32 v19, v79
	v_mul_f32_e32 v23, v0, v21
	s_nop 0
	v_mul_f32_e32 v16, v16, v23
	v_mul_f32_e32 v23, v1, v21
	v_mul_f32_e32 v17, v17, v23
	v_cvt_pk_bf16_f32 v16, v16, v17
	v_mul_f32_e32 v17, v2, v21
	v_mul_f32_e32 v17, v18, v17
	v_mul_f32_e32 v18, v3, v21
	v_mul_f32_e32 v18, v19, v18
	v_cvt_pk_bf16_f32 v17, v17, v18
	global_store_dwordx2 v[30:31], v[16:17], off
	s_nop 1
	v_mov_b32_e32 v16, v80
	v_mov_b32_e32 v17, v81
	v_mov_b32_e32 v18, v82
	v_mov_b32_e32 v19, v83
	v_mul_f32_e32 v23, v4, v21
	s_nop 0
	v_mul_f32_e32 v16, v23, v16
	v_mul_f32_e32 v23, v5, v21
	v_mul_f32_e32 v17, v23, v17
	v_cvt_pk_bf16_f32 v16, v16, v17
	v_mul_f32_e32 v17, v6, v21
	v_mul_f32_e32 v17, v17, v18
	v_mul_f32_e32 v18, v7, v21
	v_mul_f32_e32 v18, v19, v18
	v_cvt_pk_bf16_f32 v17, v17, v18
	global_store_dwordx2 v[30:31], v[16:17], off offset:512
	s_nop 1
	v_mov_b32_e32 v16, v84
	v_mov_b32_e32 v17, v85
	v_mov_b32_e32 v18, v86
	v_mov_b32_e32 v19, v87
	v_mul_f32_e32 v23, v8, v21
	s_nop 0
	v_mul_f32_e32 v16, v23, v16
	v_mul_f32_e32 v23, v9, v21
	v_mul_f32_e32 v17, v23, v17
	v_cvt_pk_bf16_f32 v16, v16, v17
	v_mul_f32_e32 v17, v10, v21
	v_mul_f32_e32 v17, v17, v18
	v_mul_f32_e32 v18, v11, v21
	v_mul_f32_e32 v18, v18, v19
	v_cvt_pk_bf16_f32 v17, v17, v18
	global_store_dwordx2 v[30:31], v[16:17], off offset:1024
	s_nop 1
	v_mov_b32_e32 v16, v88
	v_mov_b32_e32 v17, v89
	v_mov_b32_e32 v18, v90
	v_mov_b32_e32 v19, v91
	v_mul_f32_e32 v23, v12, v21
	s_nop 0
	v_mul_f32_e32 v16, v23, v16
	v_mul_f32_e32 v23, v13, v21
	v_mul_f32_e32 v17, v23, v17
	v_cvt_pk_bf16_f32 v16, v16, v17
	v_mul_f32_e32 v17, v14, v21
	v_mul_f32_e32 v17, v17, v18
	v_mul_f32_e32 v18, v15, v21
	v_mul_f32_e32 v18, v18, v19
	v_cvt_pk_bf16_f32 v17, v17, v18
	global_store_dwordx2 v[30:31], v[16:17], off offset:1536
